# adds hand-written adaLN GEMV k-loop (32 loads in flight) and attention V-tile prefetch
# baseline (speedup 1.0000x reference)
.LBB0_23:
	s_mul_hi_i32 s4, s24, 0x2aaaaaab
	s_lshr_b32 s5, s4, 31
	s_ashr_i32 s4, s4, 4
	s_add_i32 s16, s4, s5
	s_mul_i32 s4, s16, 0x60
	s_sub_i32 s4, s24, s4
	v_lshl_or_b32 v6, s4, 6, v16
	v_mad_i64_i32 v[8:9], s[4:5], s16, v20, v[2:3]
	v_ashrrev_i32_e32 v7, 31, v6
	v_lshl_add_u64 v[8:9], v[6:7], 2, v[8:9]
	s_mov_b64 s[10:11], 0
	v_mov_b32_e32 v23, v17
	v_mov_b32_e32 v22, 0
	v_mov_b32_e32 v10, 0
	v_mov_b32_e32 v11, v1
	v_mov_b32_e32 v12, 0
	v_mov_b32_e32 v13, v1
	v_readfirstlane_b32 s10, v8
	v_readfirstlane_b32 s11, v9
	s_nop 7
	global_load_dword v234, v15, s[10:11]
	s_add_u32 s10, s10, 0x6000
	s_addc_u32 s11, s11, 0
	global_load_dword v235, v15, s[10:11]
	s_add_u32 s10, s10, 0x6000
	s_addc_u32 s11, s11, 0
	global_load_dword v236, v15, s[10:11]
	s_add_u32 s10, s10, 0x6000
	s_addc_u32 s11, s11, 0
	global_load_dword v237, v15, s[10:11]
	s_add_u32 s10, s10, 0x6000
	s_addc_u32 s11, s11, 0
	global_load_dword v238, v15, s[10:11]
	s_add_u32 s10, s10, 0x6000
	s_addc_u32 s11, s11, 0
	global_load_dword v239, v15, s[10:11]
	s_add_u32 s10, s10, 0x6000
	s_addc_u32 s11, s11, 0
	global_load_dword v240, v15, s[10:11]
	s_add_u32 s10, s10, 0x6000
	s_addc_u32 s11, s11, 0
	global_load_dword v241, v15, s[10:11]
	s_add_u32 s10, s10, 0x6000
	s_addc_u32 s11, s11, 0
	global_load_dword v242, v15, s[10:11]
	s_add_u32 s10, s10, 0x6000
	s_addc_u32 s11, s11, 0
	global_load_dword v243, v15, s[10:11]
	s_add_u32 s10, s10, 0x6000
	s_addc_u32 s11, s11, 0
	global_load_dword v244, v15, s[10:11]
	s_add_u32 s10, s10, 0x6000
	s_addc_u32 s11, s11, 0
	global_load_dword v245, v15, s[10:11]
	s_add_u32 s10, s10, 0x6000
	s_addc_u32 s11, s11, 0
	global_load_dword v246, v15, s[10:11]
	s_add_u32 s10, s10, 0x6000
	s_addc_u32 s11, s11, 0
	global_load_dword v247, v15, s[10:11]
	s_add_u32 s10, s10, 0x6000
	s_addc_u32 s11, s11, 0
	global_load_dword v248, v15, s[10:11]
	s_add_u32 s10, s10, 0x6000
	s_addc_u32 s11, s11, 0
	global_load_dword v249, v15, s[10:11]
	s_add_u32 s10, s10, 0x6000
	s_addc_u32 s11, s11, 0
	global_load_dword v250, v15, s[10:11]
	s_add_u32 s10, s10, 0x6000
	s_addc_u32 s11, s11, 0
	global_load_dword v251, v15, s[10:11]
	s_add_u32 s10, s10, 0x6000
	s_addc_u32 s11, s11, 0
	global_load_dword v252, v15, s[10:11]
	s_add_u32 s10, s10, 0x6000
	s_addc_u32 s11, s11, 0
	global_load_dword v253, v15, s[10:11]
	s_add_u32 s10, s10, 0x6000
	s_addc_u32 s11, s11, 0
	global_load_dword v254, v15, s[10:11]
	s_add_u32 s10, s10, 0x6000
	s_addc_u32 s11, s11, 0
	global_load_dword v255, v15, s[10:11]
	s_add_u32 s10, s10, 0x6000
	s_addc_u32 s11, s11, 0
	global_load_dword v64, v15, s[10:11]
	s_add_u32 s10, s10, 0x6000
	s_addc_u32 s11, s11, 0
	global_load_dword v66, v15, s[10:11]
	s_add_u32 s10, s10, 0x6000
	s_addc_u32 s11, s11, 0
	global_load_dword v68, v15, s[10:11]
	s_add_u32 s10, s10, 0x6000
	s_addc_u32 s11, s11, 0
	global_load_dword v70, v15, s[10:11]
	s_add_u32 s10, s10, 0x6000
	s_addc_u32 s11, s11, 0
	global_load_dword v72, v15, s[10:11]
	s_add_u32 s10, s10, 0x6000
	s_addc_u32 s11, s11, 0
	global_load_dword v74, v15, s[10:11]
	s_add_u32 s10, s10, 0x6000
	s_addc_u32 s11, s11, 0
	global_load_dword v76, v15, s[10:11]
	s_add_u32 s10, s10, 0x6000
	s_addc_u32 s11, s11, 0
	global_load_dword v78, v15, s[10:11]
	s_add_u32 s10, s10, 0x6000
	s_addc_u32 s11, s11, 0
	global_load_dword v80, v15, s[10:11]
	s_add_u32 s10, s10, 0x6000
	s_addc_u32 s11, s11, 0
	global_load_dword v81, v15, s[10:11]
	s_add_u32 s10, s10, 0x6000
	s_addc_u32 s11, s11, 0
	s_mov_b32 s4, 7
.Lgv_loop:
	ds_read_b128 v[24:27], v23 offset:0
	ds_read_b128 v[28:31], v23 offset:16
	ds_read_b128 v[32:35], v23 offset:4096
	ds_read_b128 v[36:39], v23 offset:4112
	ds_read_b128 v[40:43], v23 offset:8192
	ds_read_b128 v[44:47], v23 offset:8208
	ds_read_b128 v[48:51], v23 offset:12288
	ds_read_b128 v[52:55], v23 offset:12304
	ds_read_b128 v[56:59], v23 offset:16384
	ds_read_b128 v[60:63], v23 offset:16400
	v_add_u32_e32 v23, 32, v23
	s_waitcnt vmcnt(24)
	s_waitcnt lgkmcnt(0)
	v_fmac_f32_e32 v10, v234, v24
	v_fmac_f32_e32 v11, v234, v32
	v_fmac_f32_e32 v12, v234, v40
	v_fmac_f32_e32 v13, v234, v48
	v_fmac_f32_e32 v22, v234, v56
	v_fmac_f32_e32 v10, v235, v25
	v_fmac_f32_e32 v11, v235, v33
	v_fmac_f32_e32 v12, v235, v41
	v_fmac_f32_e32 v13, v235, v49
	v_fmac_f32_e32 v22, v235, v57
	v_fmac_f32_e32 v10, v236, v26
	v_fmac_f32_e32 v11, v236, v34
	v_fmac_f32_e32 v12, v236, v42
	v_fmac_f32_e32 v13, v236, v50
	v_fmac_f32_e32 v22, v236, v58
	v_fmac_f32_e32 v10, v237, v27
	v_fmac_f32_e32 v11, v237, v35
	v_fmac_f32_e32 v12, v237, v43
	v_fmac_f32_e32 v13, v237, v51
	v_fmac_f32_e32 v22, v237, v59
	v_fmac_f32_e32 v10, v238, v28
	v_fmac_f32_e32 v11, v238, v36
	v_fmac_f32_e32 v12, v238, v44
	v_fmac_f32_e32 v13, v238, v52
	v_fmac_f32_e32 v22, v238, v60
	v_fmac_f32_e32 v10, v239, v29
	v_fmac_f32_e32 v11, v239, v37
	v_fmac_f32_e32 v12, v239, v45
	v_fmac_f32_e32 v13, v239, v53
	v_fmac_f32_e32 v22, v239, v61
	v_fmac_f32_e32 v10, v240, v30
	v_fmac_f32_e32 v11, v240, v38
	v_fmac_f32_e32 v12, v240, v46
	v_fmac_f32_e32 v13, v240, v54
	v_fmac_f32_e32 v22, v240, v62
	v_fmac_f32_e32 v10, v241, v31
	v_fmac_f32_e32 v11, v241, v39
	v_fmac_f32_e32 v12, v241, v47
	v_fmac_f32_e32 v13, v241, v55
	v_fmac_f32_e32 v22, v241, v63
	global_load_dword v234, v15, s[10:11]
	s_add_u32 s10, s10, 0x6000
	s_addc_u32 s11, s11, 0
	global_load_dword v235, v15, s[10:11]
	s_add_u32 s10, s10, 0x6000
	s_addc_u32 s11, s11, 0
	global_load_dword v236, v15, s[10:11]
	s_add_u32 s10, s10, 0x6000
	s_addc_u32 s11, s11, 0
	global_load_dword v237, v15, s[10:11]
	s_add_u32 s10, s10, 0x6000
	s_addc_u32 s11, s11, 0
	global_load_dword v238, v15, s[10:11]
	s_add_u32 s10, s10, 0x6000
	s_addc_u32 s11, s11, 0
	global_load_dword v239, v15, s[10:11]
	s_add_u32 s10, s10, 0x6000
	s_addc_u32 s11, s11, 0
	global_load_dword v240, v15, s[10:11]
	s_add_u32 s10, s10, 0x6000
	s_addc_u32 s11, s11, 0
	global_load_dword v241, v15, s[10:11]
	s_add_u32 s10, s10, 0x6000
	s_addc_u32 s11, s11, 0
	ds_read_b128 v[24:27], v23 offset:0
	ds_read_b128 v[28:31], v23 offset:16
	ds_read_b128 v[32:35], v23 offset:4096
	ds_read_b128 v[36:39], v23 offset:4112
	ds_read_b128 v[40:43], v23 offset:8192
	ds_read_b128 v[44:47], v23 offset:8208
	ds_read_b128 v[48:51], v23 offset:12288
	ds_read_b128 v[52:55], v23 offset:12304
	ds_read_b128 v[56:59], v23 offset:16384
	ds_read_b128 v[60:63], v23 offset:16400
	v_add_u32_e32 v23, 32, v23
	s_waitcnt vmcnt(24)
	s_waitcnt lgkmcnt(0)
	v_fmac_f32_e32 v10, v242, v24
	v_fmac_f32_e32 v11, v242, v32
	v_fmac_f32_e32 v12, v242, v40
	v_fmac_f32_e32 v13, v242, v48
	v_fmac_f32_e32 v22, v242, v56
	v_fmac_f32_e32 v10, v243, v25
	v_fmac_f32_e32 v11, v243, v33
	v_fmac_f32_e32 v12, v243, v41
	v_fmac_f32_e32 v13, v243, v49
	v_fmac_f32_e32 v22, v243, v57
	v_fmac_f32_e32 v10, v244, v26
	v_fmac_f32_e32 v11, v244, v34
	v_fmac_f32_e32 v12, v244, v42
	v_fmac_f32_e32 v13, v244, v50
	v_fmac_f32_e32 v22, v244, v58
	v_fmac_f32_e32 v10, v245, v27
	v_fmac_f32_e32 v11, v245, v35
	v_fmac_f32_e32 v12, v245, v43
	v_fmac_f32_e32 v13, v245, v51
	v_fmac_f32_e32 v22, v245, v59
	v_fmac_f32_e32 v10, v246, v28
	v_fmac_f32_e32 v11, v246, v36
	v_fmac_f32_e32 v12, v246, v44
	v_fmac_f32_e32 v13, v246, v52
	v_fmac_f32_e32 v22, v246, v60
	v_fmac_f32_e32 v10, v247, v29
	v_fmac_f32_e32 v11, v247, v37
	v_fmac_f32_e32 v12, v247, v45
	v_fmac_f32_e32 v13, v247, v53
	v_fmac_f32_e32 v22, v247, v61
	v_fmac_f32_e32 v10, v248, v30
	v_fmac_f32_e32 v11, v248, v38
	v_fmac_f32_e32 v12, v248, v46
	v_fmac_f32_e32 v13, v248, v54
	v_fmac_f32_e32 v22, v248, v62
	v_fmac_f32_e32 v10, v249, v31
	v_fmac_f32_e32 v11, v249, v39
	v_fmac_f32_e32 v12, v249, v47
	v_fmac_f32_e32 v13, v249, v55
	v_fmac_f32_e32 v22, v249, v63
	global_load_dword v242, v15, s[10:11]
	s_add_u32 s10, s10, 0x6000
	s_addc_u32 s11, s11, 0
	global_load_dword v243, v15, s[10:11]
	s_add_u32 s10, s10, 0x6000
	s_addc_u32 s11, s11, 0
	global_load_dword v244, v15, s[10:11]
	s_add_u32 s10, s10, 0x6000
	s_addc_u32 s11, s11, 0
	global_load_dword v245, v15, s[10:11]
	s_add_u32 s10, s10, 0x6000
	s_addc_u32 s11, s11, 0
	global_load_dword v246, v15, s[10:11]
	s_add_u32 s10, s10, 0x6000
	s_addc_u32 s11, s11, 0
	global_load_dword v247, v15, s[10:11]
	s_add_u32 s10, s10, 0x6000
	s_addc_u32 s11, s11, 0
	global_load_dword v248, v15, s[10:11]
	s_add_u32 s10, s10, 0x6000
	s_addc_u32 s11, s11, 0
	global_load_dword v249, v15, s[10:11]
	s_add_u32 s10, s10, 0x6000
	s_addc_u32 s11, s11, 0
	ds_read_b128 v[24:27], v23 offset:0
	ds_read_b128 v[28:31], v23 offset:16
	ds_read_b128 v[32:35], v23 offset:4096
	ds_read_b128 v[36:39], v23 offset:4112
	ds_read_b128 v[40:43], v23 offset:8192
	ds_read_b128 v[44:47], v23 offset:8208
	ds_read_b128 v[48:51], v23 offset:12288
	ds_read_b128 v[52:55], v23 offset:12304
	ds_read_b128 v[56:59], v23 offset:16384
	ds_read_b128 v[60:63], v23 offset:16400
	v_add_u32_e32 v23, 32, v23
	s_waitcnt vmcnt(24)
	s_waitcnt lgkmcnt(0)
	v_fmac_f32_e32 v10, v250, v24
	v_fmac_f32_e32 v11, v250, v32
	v_fmac_f32_e32 v12, v250, v40
	v_fmac_f32_e32 v13, v250, v48
	v_fmac_f32_e32 v22, v250, v56
	v_fmac_f32_e32 v10, v251, v25
	v_fmac_f32_e32 v11, v251, v33
	v_fmac_f32_e32 v12, v251, v41
	v_fmac_f32_e32 v13, v251, v49
	v_fmac_f32_e32 v22, v251, v57
	v_fmac_f32_e32 v10, v252, v26
	v_fmac_f32_e32 v11, v252, v34
	v_fmac_f32_e32 v12, v252, v42
	v_fmac_f32_e32 v13, v252, v50
	v_fmac_f32_e32 v22, v252, v58
	v_fmac_f32_e32 v10, v253, v27
	v_fmac_f32_e32 v11, v253, v35
	v_fmac_f32_e32 v12, v253, v43
	v_fmac_f32_e32 v13, v253, v51
	v_fmac_f32_e32 v22, v253, v59
	v_fmac_f32_e32 v10, v254, v28
	v_fmac_f32_e32 v11, v254, v36
	v_fmac_f32_e32 v12, v254, v44
	v_fmac_f32_e32 v13, v254, v52
	v_fmac_f32_e32 v22, v254, v60
	v_fmac_f32_e32 v10, v255, v29
	v_fmac_f32_e32 v11, v255, v37
	v_fmac_f32_e32 v12, v255, v45
	v_fmac_f32_e32 v13, v255, v53
	v_fmac_f32_e32 v22, v255, v61
	v_fmac_f32_e32 v10, v64, v30
	v_fmac_f32_e32 v11, v64, v38
	v_fmac_f32_e32 v12, v64, v46
	v_fmac_f32_e32 v13, v64, v54
	v_fmac_f32_e32 v22, v64, v62
	v_fmac_f32_e32 v10, v66, v31
	v_fmac_f32_e32 v11, v66, v39
	v_fmac_f32_e32 v12, v66, v47
	v_fmac_f32_e32 v13, v66, v55
	v_fmac_f32_e32 v22, v66, v63
	global_load_dword v250, v15, s[10:11]
	s_add_u32 s10, s10, 0x6000
	s_addc_u32 s11, s11, 0
	global_load_dword v251, v15, s[10:11]
	s_add_u32 s10, s10, 0x6000
	s_addc_u32 s11, s11, 0
	global_load_dword v252, v15, s[10:11]
	s_add_u32 s10, s10, 0x6000
	s_addc_u32 s11, s11, 0
	global_load_dword v253, v15, s[10:11]
	s_add_u32 s10, s10, 0x6000
	s_addc_u32 s11, s11, 0
	global_load_dword v254, v15, s[10:11]
	s_add_u32 s10, s10, 0x6000
	s_addc_u32 s11, s11, 0
	global_load_dword v255, v15, s[10:11]
	s_add_u32 s10, s10, 0x6000
	s_addc_u32 s11, s11, 0
	global_load_dword v64, v15, s[10:11]
	s_add_u32 s10, s10, 0x6000
	s_addc_u32 s11, s11, 0
	global_load_dword v66, v15, s[10:11]
	s_add_u32 s10, s10, 0x6000
	s_addc_u32 s11, s11, 0
	ds_read_b128 v[24:27], v23 offset:0
	ds_read_b128 v[28:31], v23 offset:16
	ds_read_b128 v[32:35], v23 offset:4096
	ds_read_b128 v[36:39], v23 offset:4112
	ds_read_b128 v[40:43], v23 offset:8192
	ds_read_b128 v[44:47], v23 offset:8208
	ds_read_b128 v[48:51], v23 offset:12288
	ds_read_b128 v[52:55], v23 offset:12304
	ds_read_b128 v[56:59], v23 offset:16384
	ds_read_b128 v[60:63], v23 offset:16400
	v_add_u32_e32 v23, 32, v23
	s_waitcnt vmcnt(24)
	s_waitcnt lgkmcnt(0)
	v_fmac_f32_e32 v10, v68, v24
	v_fmac_f32_e32 v11, v68, v32
	v_fmac_f32_e32 v12, v68, v40
	v_fmac_f32_e32 v13, v68, v48
	v_fmac_f32_e32 v22, v68, v56
	v_fmac_f32_e32 v10, v70, v25
	v_fmac_f32_e32 v11, v70, v33
	v_fmac_f32_e32 v12, v70, v41
	v_fmac_f32_e32 v13, v70, v49
	v_fmac_f32_e32 v22, v70, v57
	v_fmac_f32_e32 v10, v72, v26
	v_fmac_f32_e32 v11, v72, v34
	v_fmac_f32_e32 v12, v72, v42
	v_fmac_f32_e32 v13, v72, v50
	v_fmac_f32_e32 v22, v72, v58
	v_fmac_f32_e32 v10, v74, v27
	v_fmac_f32_e32 v11, v74, v35
	v_fmac_f32_e32 v12, v74, v43
	v_fmac_f32_e32 v13, v74, v51
	v_fmac_f32_e32 v22, v74, v59
	v_fmac_f32_e32 v10, v76, v28
	v_fmac_f32_e32 v11, v76, v36
	v_fmac_f32_e32 v12, v76, v44
	v_fmac_f32_e32 v13, v76, v52
	v_fmac_f32_e32 v22, v76, v60
	v_fmac_f32_e32 v10, v78, v29
	v_fmac_f32_e32 v11, v78, v37
	v_fmac_f32_e32 v12, v78, v45
	v_fmac_f32_e32 v13, v78, v53
	v_fmac_f32_e32 v22, v78, v61
	v_fmac_f32_e32 v10, v80, v30
	v_fmac_f32_e32 v11, v80, v38
	v_fmac_f32_e32 v12, v80, v46
	v_fmac_f32_e32 v13, v80, v54
	v_fmac_f32_e32 v22, v80, v62
	v_fmac_f32_e32 v10, v81, v31
	v_fmac_f32_e32 v11, v81, v39
	v_fmac_f32_e32 v12, v81, v47
	v_fmac_f32_e32 v13, v81, v55
	v_fmac_f32_e32 v22, v81, v63
	global_load_dword v68, v15, s[10:11]
	s_add_u32 s10, s10, 0x6000
	s_addc_u32 s11, s11, 0
	global_load_dword v70, v15, s[10:11]
	s_add_u32 s10, s10, 0x6000
	s_addc_u32 s11, s11, 0
	global_load_dword v72, v15, s[10:11]
	s_add_u32 s10, s10, 0x6000
	s_addc_u32 s11, s11, 0
	global_load_dword v74, v15, s[10:11]
	s_add_u32 s10, s10, 0x6000
	s_addc_u32 s11, s11, 0
	global_load_dword v76, v15, s[10:11]
	s_add_u32 s10, s10, 0x6000
	s_addc_u32 s11, s11, 0
	global_load_dword v78, v15, s[10:11]
	s_add_u32 s10, s10, 0x6000
	s_addc_u32 s11, s11, 0
	global_load_dword v80, v15, s[10:11]
	s_add_u32 s10, s10, 0x6000
	s_addc_u32 s11, s11, 0
	global_load_dword v81, v15, s[10:11]
	s_add_u32 s10, s10, 0x6000
	s_addc_u32 s11, s11, 0
	s_sub_u32 s4, s4, 1
	s_cmp_lg_u32 s4, 0
	s_cbranch_scc1 .Lgv_loop
	ds_read_b128 v[24:27], v23 offset:0
	ds_read_b128 v[28:31], v23 offset:16
	ds_read_b128 v[32:35], v23 offset:4096
	ds_read_b128 v[36:39], v23 offset:4112
	ds_read_b128 v[40:43], v23 offset:8192
	ds_read_b128 v[44:47], v23 offset:8208
	ds_read_b128 v[48:51], v23 offset:12288
	ds_read_b128 v[52:55], v23 offset:12304
	ds_read_b128 v[56:59], v23 offset:16384
	ds_read_b128 v[60:63], v23 offset:16400
	v_add_u32_e32 v23, 32, v23
	s_waitcnt vmcnt(24)
	s_waitcnt lgkmcnt(0)
	v_fmac_f32_e32 v10, v234, v24
	v_fmac_f32_e32 v11, v234, v32
	v_fmac_f32_e32 v12, v234, v40
	v_fmac_f32_e32 v13, v234, v48
	v_fmac_f32_e32 v22, v234, v56
	v_fmac_f32_e32 v10, v235, v25
	v_fmac_f32_e32 v11, v235, v33
	v_fmac_f32_e32 v12, v235, v41
	v_fmac_f32_e32 v13, v235, v49
	v_fmac_f32_e32 v22, v235, v57
	v_fmac_f32_e32 v10, v236, v26
	v_fmac_f32_e32 v11, v236, v34
	v_fmac_f32_e32 v12, v236, v42
	v_fmac_f32_e32 v13, v236, v50
	v_fmac_f32_e32 v22, v236, v58
	v_fmac_f32_e32 v10, v237, v27
	v_fmac_f32_e32 v11, v237, v35
	v_fmac_f32_e32 v12, v237, v43
	v_fmac_f32_e32 v13, v237, v51
	v_fmac_f32_e32 v22, v237, v59
	v_fmac_f32_e32 v10, v238, v28
	v_fmac_f32_e32 v11, v238, v36
	v_fmac_f32_e32 v12, v238, v44
	v_fmac_f32_e32 v13, v238, v52
	v_fmac_f32_e32 v22, v238, v60
	v_fmac_f32_e32 v10, v239, v29
	v_fmac_f32_e32 v11, v239, v37
	v_fmac_f32_e32 v12, v239, v45
	v_fmac_f32_e32 v13, v239, v53
	v_fmac_f32_e32 v22, v239, v61
	v_fmac_f32_e32 v10, v240, v30
	v_fmac_f32_e32 v11, v240, v38
	v_fmac_f32_e32 v12, v240, v46
	v_fmac_f32_e32 v13, v240, v54
	v_fmac_f32_e32 v22, v240, v62
	v_fmac_f32_e32 v10, v241, v31
	v_fmac_f32_e32 v11, v241, v39
	v_fmac_f32_e32 v12, v241, v47
	v_fmac_f32_e32 v13, v241, v55
	v_fmac_f32_e32 v22, v241, v63
	ds_read_b128 v[24:27], v23 offset:0
	ds_read_b128 v[28:31], v23 offset:16
	ds_read_b128 v[32:35], v23 offset:4096
	ds_read_b128 v[36:39], v23 offset:4112
	ds_read_b128 v[40:43], v23 offset:8192
	ds_read_b128 v[44:47], v23 offset:8208
	ds_read_b128 v[48:51], v23 offset:12288
	ds_read_b128 v[52:55], v23 offset:12304
	ds_read_b128 v[56:59], v23 offset:16384
	ds_read_b128 v[60:63], v23 offset:16400
	v_add_u32_e32 v23, 32, v23
	s_waitcnt vmcnt(16)
	s_waitcnt lgkmcnt(0)
	v_fmac_f32_e32 v10, v242, v24
	v_fmac_f32_e32 v11, v242, v32
	v_fmac_f32_e32 v12, v242, v40
	v_fmac_f32_e32 v13, v242, v48
	v_fmac_f32_e32 v22, v242, v56
	v_fmac_f32_e32 v10, v243, v25
	v_fmac_f32_e32 v11, v243, v33
	v_fmac_f32_e32 v12, v243, v41
	v_fmac_f32_e32 v13, v243, v49
	v_fmac_f32_e32 v22, v243, v57
	v_fmac_f32_e32 v10, v244, v26
	v_fmac_f32_e32 v11, v244, v34
	v_fmac_f32_e32 v12, v244, v42
	v_fmac_f32_e32 v13, v244, v50
	v_fmac_f32_e32 v22, v244, v58
	v_fmac_f32_e32 v10, v245, v27
	v_fmac_f32_e32 v11, v245, v35
	v_fmac_f32_e32 v12, v245, v43
	v_fmac_f32_e32 v13, v245, v51
	v_fmac_f32_e32 v22, v245, v59
	v_fmac_f32_e32 v10, v246, v28
	v_fmac_f32_e32 v11, v246, v36
	v_fmac_f32_e32 v12, v246, v44
	v_fmac_f32_e32 v13, v246, v52
	v_fmac_f32_e32 v22, v246, v60
	v_fmac_f32_e32 v10, v247, v29
	v_fmac_f32_e32 v11, v247, v37
	v_fmac_f32_e32 v12, v247, v45
	v_fmac_f32_e32 v13, v247, v53
	v_fmac_f32_e32 v22, v247, v61
	v_fmac_f32_e32 v10, v248, v30
	v_fmac_f32_e32 v11, v248, v38
	v_fmac_f32_e32 v12, v248, v46
	v_fmac_f32_e32 v13, v248, v54
	v_fmac_f32_e32 v22, v248, v62
	v_fmac_f32_e32 v10, v249, v31
	v_fmac_f32_e32 v11, v249, v39
	v_fmac_f32_e32 v12, v249, v47
	v_fmac_f32_e32 v13, v249, v55
	v_fmac_f32_e32 v22, v249, v63
	ds_read_b128 v[24:27], v23 offset:0
	ds_read_b128 v[28:31], v23 offset:16
	ds_read_b128 v[32:35], v23 offset:4096
	ds_read_b128 v[36:39], v23 offset:4112
	ds_read_b128 v[40:43], v23 offset:8192
	ds_read_b128 v[44:47], v23 offset:8208
	ds_read_b128 v[48:51], v23 offset:12288
	ds_read_b128 v[52:55], v23 offset:12304
	ds_read_b128 v[56:59], v23 offset:16384
	ds_read_b128 v[60:63], v23 offset:16400
	v_add_u32_e32 v23, 32, v23
	s_waitcnt vmcnt(8)
	s_waitcnt lgkmcnt(0)
	v_fmac_f32_e32 v10, v250, v24
	v_fmac_f32_e32 v11, v250, v32
	v_fmac_f32_e32 v12, v250, v40
	v_fmac_f32_e32 v13, v250, v48
	v_fmac_f32_e32 v22, v250, v56
	v_fmac_f32_e32 v10, v251, v25
	v_fmac_f32_e32 v11, v251, v33
	v_fmac_f32_e32 v12, v251, v41
	v_fmac_f32_e32 v13, v251, v49
	v_fmac_f32_e32 v22, v251, v57
	v_fmac_f32_e32 v10, v252, v26
	v_fmac_f32_e32 v11, v252, v34
	v_fmac_f32_e32 v12, v252, v42
	v_fmac_f32_e32 v13, v252, v50
	v_fmac_f32_e32 v22, v252, v58
	v_fmac_f32_e32 v10, v253, v27
	v_fmac_f32_e32 v11, v253, v35
	v_fmac_f32_e32 v12, v253, v43
	v_fmac_f32_e32 v13, v253, v51
	v_fmac_f32_e32 v22, v253, v59
	v_fmac_f32_e32 v10, v254, v28
	v_fmac_f32_e32 v11, v254, v36
	v_fmac_f32_e32 v12, v254, v44
	v_fmac_f32_e32 v13, v254, v52
	v_fmac_f32_e32 v22, v254, v60
	v_fmac_f32_e32 v10, v255, v29
	v_fmac_f32_e32 v11, v255, v37
	v_fmac_f32_e32 v12, v255, v45
	v_fmac_f32_e32 v13, v255, v53
	v_fmac_f32_e32 v22, v255, v61
	v_fmac_f32_e32 v10, v64, v30
	v_fmac_f32_e32 v11, v64, v38
	v_fmac_f32_e32 v12, v64, v46
	v_fmac_f32_e32 v13, v64, v54
	v_fmac_f32_e32 v22, v64, v62
	v_fmac_f32_e32 v10, v66, v31
	v_fmac_f32_e32 v11, v66, v39
	v_fmac_f32_e32 v12, v66, v47
	v_fmac_f32_e32 v13, v66, v55
	v_fmac_f32_e32 v22, v66, v63
	ds_read_b128 v[24:27], v23 offset:0
	ds_read_b128 v[28:31], v23 offset:16
	ds_read_b128 v[32:35], v23 offset:4096
	ds_read_b128 v[36:39], v23 offset:4112
	ds_read_b128 v[40:43], v23 offset:8192
	ds_read_b128 v[44:47], v23 offset:8208
	ds_read_b128 v[48:51], v23 offset:12288
	ds_read_b128 v[52:55], v23 offset:12304
	ds_read_b128 v[56:59], v23 offset:16384
	ds_read_b128 v[60:63], v23 offset:16400
	v_add_u32_e32 v23, 32, v23
	s_waitcnt vmcnt(0)
	s_waitcnt lgkmcnt(0)
	v_fmac_f32_e32 v10, v68, v24
	v_fmac_f32_e32 v11, v68, v32
	v_fmac_f32_e32 v12, v68, v40
	v_fmac_f32_e32 v13, v68, v48
	v_fmac_f32_e32 v22, v68, v56
	v_fmac_f32_e32 v10, v70, v25
	v_fmac_f32_e32 v11, v70, v33
	v_fmac_f32_e32 v12, v70, v41
	v_fmac_f32_e32 v13, v70, v49
	v_fmac_f32_e32 v22, v70, v57
	v_fmac_f32_e32 v10, v72, v26
	v_fmac_f32_e32 v11, v72, v34
	v_fmac_f32_e32 v12, v72, v42
	v_fmac_f32_e32 v13, v72, v50
	v_fmac_f32_e32 v22, v72, v58
	v_fmac_f32_e32 v10, v74, v27
	v_fmac_f32_e32 v11, v74, v35
	v_fmac_f32_e32 v12, v74, v43
	v_fmac_f32_e32 v13, v74, v51
	v_fmac_f32_e32 v22, v74, v59
	v_fmac_f32_e32 v10, v76, v28
	v_fmac_f32_e32 v11, v76, v36
	v_fmac_f32_e32 v12, v76, v44
	v_fmac_f32_e32 v13, v76, v52
	v_fmac_f32_e32 v22, v76, v60
	v_fmac_f32_e32 v10, v78, v29
	v_fmac_f32_e32 v11, v78, v37
	v_fmac_f32_e32 v12, v78, v45
	v_fmac_f32_e32 v13, v78, v53
	v_fmac_f32_e32 v22, v78, v61
	v_fmac_f32_e32 v10, v80, v30
	v_fmac_f32_e32 v11, v80, v38
	v_fmac_f32_e32 v12, v80, v46
	v_fmac_f32_e32 v13, v80, v54
	v_fmac_f32_e32 v22, v80, v62
	v_fmac_f32_e32 v10, v81, v31
	v_fmac_f32_e32 v11, v81, v39
	v_fmac_f32_e32 v12, v81, v47
	v_fmac_f32_e32 v13, v81, v55
	v_fmac_f32_e32 v22, v81, v63
	ds_write_b32 v18, v10 offset:20480
	ds_write2st64_b32 v19, v11, v12 offset0:81 offset1:82
	ds_write2st64_b32 v19, v13, v22 offset0:83 offset1:84
	s_waitcnt lgkmcnt(0)
	s_barrier
	s_and_saveexec_b64 s[10:11], vcc
	s_cbranch_execz .LBB0_22
	s_load_dwordx2 s[4:5], s[14:15], 0x48
	s_mul_i32 s25, s16, 0x6000
	s_mul_hi_i32 s17, s16, 0x6000
	v_lshlrev_b64 v[8:9], 2, v[6:7]
	v_mov_b32_e32 v10, v0
	s_waitcnt lgkmcnt(0)
	s_add_u32 s4, s4, s25
	s_addc_u32 s5, s5, s17
	v_lshl_add_u64 v[6:7], s[4:5], 0, v[8:9]
	v_mad_i64_i32 v[8:9], s[4:5], s16, v21, v[8:9]
	v_lshl_add_u64 v[8:9], v[4:5], 0, v[8:9]
	s_mov_b64 s[16:17], 0
	v_mov_b32_e32 v11, v162

.LBB0_612:
	s_add_u32 s12, s64, s26
	v_add_u32_e32 v148, s41, v159
	s_addc_u32 s26, s65, s27
	v_ashrrev_i32_e32 v149, 31, v148
	s_add_u32 s24, s12, s24
	v_lshlrev_b64 v[0:1], 11, v[148:149]
	s_addc_u32 s25, s26, s25
	v_lshl_add_u64 v[0:1], s[14:15], 0, v[0:1]
	s_lshl_b32 s12, s39, 8
	v_lshl_add_u64 v[0:1], v[0:1], 0, s[12:13]
	v_lshl_add_u64 v[0:1], v[0:1], 0, v[130:131]
	v_mov_b32_e32 v139, v131
	v_lshl_add_u64 v[0:1], v[0:1], 0, v[138:139]
	global_load_dwordx4 v[72:75], v[0:1], off
	global_load_dwordx4 v[68:71], v[0:1], off offset:64
	v_add_co_u32_e32 v0, vcc, s29, v0
	v_mov_b32_e32 v141, v131
	s_nop 0
	v_addc_co_u32_e32 v1, vcc, 0, v1, vcc
	global_load_dwordx4 v[76:79], v[0:1], off
	global_load_dwordx4 v[64:67], v[0:1], off offset:64
	v_lshl_add_u64 v[0:1], s[8:9], 0, v[140:141]
	v_mov_b32_e32 v143, v131
	v_lshl_add_u64 v[150:151], v[0:1], 0, v[142:143]
	v_add_co_u32_e32 v0, vcc, s30, v150
	global_load_dwordx4 v[80:83], v[150:151], off
	s_nop 0
	v_addc_co_u32_e32 v1, vcc, 0, v151, vcc
	v_add_co_u32_e32 v2, vcc, s31, v150
	global_load_dwordx4 v[88:91], v[0:1], off
	s_nop 0
	v_addc_co_u32_e32 v3, vcc, 0, v151, vcc
	global_load_dwordx4 v[84:87], v[0:1], off offset:-4096
	global_load_dwordx4 v[92:95], v[2:3], off
	v_mul_u32_u24_e32 v0, s40, v147
	v_lshlrev_b32_e32 v0, 1, v0
	v_mov_b32_e32 v1, v131
	v_lshl_add_u64 v[0:1], s[24:25], 0, v[0:1]
	v_mov_b32_e32 v145, v131
	v_cmp_lt_i32_e32 vcc, v172, v173
	v_lshl_add_u64 v[152:153], v[0:1], 0, v[144:145]
	s_lshl_b32 s8, s40, 8
	v_cndmask_b32_e32 v0, v157, v172, vcc
	v_cmp_lt_i32_e32 vcc, v174, v173
	v_lshlrev_b32_e32 v139, 2, v0
	v_mov_b32_e32 v8, v131
	v_cndmask_b32_e32 v0, v157, v174, vcc
	v_mov_b32_e32 v9, v131
	v_mov_b32_e32 v10, v131
	v_mov_b32_e32 v11, v131
	v_lshlrev_b32_e32 v135, 2, v0
	s_and_b32 s8, s8, 0x7c000
	v_mov_b64_e32 v[26:27], v[10:11]
	v_mov_b64_e32 v[30:31], v[10:11]
	v_mov_b64_e32 v[42:43], v[10:11]
	v_mov_b64_e32 v[46:47], v[10:11]
	v_mov_b64_e32 v[58:59], v[10:11]
	v_mov_b64_e32 v[0:1], v[8:9]
	v_mov_b64_e32 v[14:15], v[10:11]
	v_mov_b64_e32 v[22:23], v[10:11]
	v_mov_b64_e32 v[34:35], v[10:11]
	v_mov_b64_e32 v[38:39], v[10:11]
	v_mov_b64_e32 v[50:51], v[10:11]
	v_mov_b64_e32 v[54:55], v[10:11]
	v_mov_b64_e32 v[62:63], v[10:11]
	v_mov_b64_e32 v[18:19], v[10:11]
	v_mov_b64_e32 v[4:5], v[8:9]
	s_lshl_b32 s39, s39, 7
	s_lshl_b32 s12, s40, 6
	s_add_u32 s41, s8, 0xffffc000
	s_lshl_b32 s8, s40, 7
	s_mov_b32 s9, s13
	s_mul_i32 s24, s40, 0xc0
	s_mov_b32 s25, s13
	v_mov_b32_e32 v145, 0
	v_mov_b32_e32 v158, 0xf149f2ca
	s_mov_b64 s[26:27], 0
	v_mov_b64_e32 v[154:155], v[152:153]
	v_mov_b64_e32 v[24:25], v[8:9]
	v_mov_b64_e32 v[28:29], v[8:9]
	v_mov_b64_e32 v[40:41], v[8:9]
	v_mov_b64_e32 v[44:45], v[8:9]
	v_mov_b64_e32 v[56:57], v[8:9]
	v_mov_b64_e32 v[2:3], v[10:11]
	v_mov_b64_e32 v[12:13], v[8:9]
	v_mov_b64_e32 v[20:21], v[8:9]
	v_mov_b64_e32 v[32:33], v[8:9]
	v_mov_b64_e32 v[36:37], v[8:9]
	v_mov_b64_e32 v[48:49], v[8:9]
	v_mov_b64_e32 v[52:53], v[8:9]
	v_mov_b64_e32 v[60:61], v[8:9]
	v_mov_b32_e32 v141, 0xf149f2ca
	v_mov_b32_e32 v143, 0
	v_mov_b64_e32 v[16:17], v[8:9]
	v_mov_b64_e32 v[6:7], v[10:11]
	global_load_dwordx4 v[220:223], v[154:155], off
	v_lshl_add_u64 v[236:237], v[154:155], 0, s[12:13]
	global_load_dwordx4 v[224:227], v[236:237], off
	v_lshl_add_u64 v[236:237], v[154:155], 0, s[8:9]
	global_load_dwordx4 v[228:231], v[236:237], off
	v_lshl_add_u64 v[236:237], v[154:155], 0, s[24:25]
	global_load_dwordx4 v[232:235], v[236:237], off
.LBB0_613:
	s_barrier
	s_waitcnt vmcnt(7)
	ds_write_b128 v161, v[80:83]
	s_waitcnt vmcnt(5)
	ds_write_b128 v161, v[84:87] offset:4096
	ds_write_b128 v161, v[88:91] offset:8192
	s_waitcnt vmcnt(4)
	ds_write_b128 v161, v[92:95] offset:12288
	s_waitcnt vmcnt(3)
	ds_write_b128 v167, v[220:223] offset:16384
	s_waitcnt vmcnt(2)
	ds_write_b128 v167, v[224:227] offset:20480
	s_waitcnt vmcnt(1)
	ds_write_b128 v167, v[228:231] offset:24576
	s_waitcnt vmcnt(0)
	ds_write_b128 v167, v[232:235] offset:28672
	s_waitcnt lgkmcnt(0)
	s_barrier
	ds_read_b128 v[80:83], v170
	ds_read_b128 v[84:87], v170 offset:4096
	s_waitcnt lgkmcnt(0)
	v_mfma_f32_16x16x32_bf16 v[92:95], v[84:87], v[72:75], 0
	v_mfma_f32_16x16x32_bf16 v[104:107], v[84:87], v[76:79], 0
	ds_read_b128 v[84:87], v170 offset:8192
	ds_read_b128 v[96:99], v170 offset:12288
	ds_read_b128 v[184:187], v171 offset:4096
	ds_read_b128 v[188:191], v171 offset:8192
	s_waitcnt lgkmcnt(3)
	v_mfma_f32_16x16x32_bf16 v[100:103], v[84:87], v[72:75], 0
	v_mfma_f32_16x16x32_bf16 v[120:123], v[84:87], v[76:79], 0
	ds_read_b128 v[84:87], v171
	v_mfma_f32_16x16x32_bf16 v[88:91], v[80:83], v[72:75], 0
	s_waitcnt lgkmcnt(3)
	v_mfma_f32_16x16x32_bf16 v[124:127], v[96:99], v[72:75], 0
	v_mfma_f32_16x16x32_bf16 v[180:183], v[96:99], v[76:79], 0
	v_lshl_add_u64 v[96:97], v[150:151], 0, s[26:27]
	v_mfma_f32_16x16x32_bf16 v[80:83], v[80:83], v[76:79], 0
	s_waitcnt lgkmcnt(0)
	v_mfma_f32_16x16x32_bf16 v[112:115], v[84:87], v[68:71], v[88:91]
	s_nop 2
	v_add_co_u32_e32 v88, vcc, s34, v96
	v_mfma_f32_16x16x32_bf16 v[116:119], v[84:87], v[64:67], v[80:83]
	s_nop 0
	v_addc_co_u32_e32 v89, vcc, 0, v97, vcc
	v_add_co_u32_e32 v96, vcc, s35, v96
	v_mfma_f32_16x16x32_bf16 v[108:111], v[184:187], v[68:71], v[92:95]
	s_nop 0
	v_addc_co_u32_e32 v97, vcc, 0, v97, vcc
	global_load_dwordx4 v[80:83], v[88:89], off offset:-4096
	global_load_dwordx4 v[84:87], v[88:89], off
	ds_read_b128 v[192:195], v171 offset:12288
	global_load_dwordx4 v[88:91], v[96:97], off offset:-4096
	global_load_dwordx4 v[92:95], v[96:97], off
	global_load_dwordx4 v[220:223], v[154:155], off offset:128
	v_lshl_add_u64 v[236:237], v[154:155], 0, s[12:13]
	global_load_dwordx4 v[224:227], v[236:237], off offset:128
	v_lshl_add_u64 v[236:237], v[154:155], 0, s[8:9]
	global_load_dwordx4 v[228:231], v[236:237], off offset:128
	v_lshl_add_u64 v[236:237], v[154:155], 0, s[24:25]
	global_load_dwordx4 v[232:235], v[236:237], off offset:128
	s_waitcnt lgkmcnt(0)
	v_mfma_f32_16x16x32_bf16 v[96:99], v[192:195], v[68:71], v[124:127]
	s_nop 2
	v_max_f32_e32 v124, v113, v113
	v_max_f32_e32 v125, v112, v112
	v_max_f32_e32 v124, v125, v124
	v_mfma_f32_16x16x32_bf16 v[100:103], v[188:191], v[68:71], v[100:103]
	v_max3_f32 v124, v124, v114, v115
	v_max3_f32 v124, v124, v108, v109
	v_max3_f32 v124, v124, v110, v111
	v_mfma_f32_16x16x32_bf16 v[120:123], v[188:191], v[64:67], v[120:123]
	s_nop 3
	v_max3_f32 v124, v124, v100, v101
	v_max3_f32 v124, v124, v102, v103
	v_max3_f32 v124, v124, v96, v97
	v_max3_f32 v124, v124, v98, v99
	v_mul_f32_e32 v156, 0x3e38aa3b, v124
	ds_bpermute_b32 v196, v139, v156
	v_mfma_f32_16x16x32_bf16 v[124:127], v[184:187], v[64:67], v[104:107]
	s_waitcnt lgkmcnt(0)
	s_nop 1
	v_max_f32_e32 v104, v196, v196
	v_max_f32_e32 v104, v156, v104
	ds_bpermute_b32 v105, v135, v104
	v_mov_b32_e32 v106, v141
	s_waitcnt lgkmcnt(0)
	v_max_f32_e32 v105, v105, v105
	v_max_f32_e32 v104, v104, v105
	v_add_f32_e32 v105, 0x41000000, v106
	v_cmp_gt_f32_e32 vcc, v104, v105
	s_nop 1
	v_cndmask_b32_e32 v141, v106, v104, vcc
	v_sub_f32_e32 v104, v106, v141
	v_exp_f32_e32 v156, v104
	v_mfma_f32_16x16x32_bf16 v[104:107], v[192:195], v[64:67], v[180:183]
	v_cndmask_b32_e32 v156, 1.0, v156, vcc
	s_cbranch_vccz .LBB0_615
	v_pk_mul_f32 v[62:63], v[62:63], v[156:157] op_sel_hi:[1,0]
	v_pk_mul_f32 v[60:61], v[60:61], v[156:157] op_sel_hi:[1,0]
	v_pk_mul_f32 v[54:55], v[54:55], v[156:157] op_sel_hi:[1,0]
	v_pk_mul_f32 v[52:53], v[52:53], v[156:157] op_sel_hi:[1,0]
	v_pk_mul_f32 v[50:51], v[50:51], v[156:157] op_sel_hi:[1,0]
	v_pk_mul_f32 v[48:49], v[48:49], v[156:157] op_sel_hi:[1,0]
	v_pk_mul_f32 v[38:39], v[38:39], v[156:157] op_sel_hi:[1,0]
	v_pk_mul_f32 v[36:37], v[36:37], v[156:157] op_sel_hi:[1,0]
	v_pk_mul_f32 v[34:35], v[34:35], v[156:157] op_sel_hi:[1,0]
	v_pk_mul_f32 v[32:33], v[32:33], v[156:157] op_sel_hi:[1,0]
	v_pk_mul_f32 v[22:23], v[22:23], v[156:157] op_sel_hi:[1,0]
	v_pk_mul_f32 v[20:21], v[20:21], v[156:157] op_sel_hi:[1,0]
	v_pk_mul_f32 v[14:15], v[14:15], v[156:157] op_sel_hi:[1,0]
	v_pk_mul_f32 v[12:13], v[12:13], v[156:157] op_sel_hi:[1,0]
	v_pk_mul_f32 v[2:3], v[2:3], v[156:157] op_sel_hi:[1,0]
	v_pk_mul_f32 v[0:1], v[0:1], v[156:157] op_sel_hi:[1,0]

.LBB0_619:
	s_and_b32 s8, s40, 0x7c0
	s_sub_i32 s8, s8, 64
	s_mov_b32 s9, s13
	v_lshl_add_u64 v[100:101], s[8:9], 1, v[152:153]
	v_lshl_add_u64 v[108:109], v[100:101], 0, s[12:13]
	s_barrier
	s_nop 0
	v_lshl_add_u64 v[108:109], v[108:109], 0, s[12:13]
	v_lshl_add_u64 v[112:113], v[108:109], 0, s[12:13]
	s_nop 0
	s_waitcnt vmcnt(7)
	ds_write_b128 v161, v[80:83]
	s_waitcnt vmcnt(6)
	ds_write_b128 v161, v[84:87] offset:4096
	s_waitcnt vmcnt(5)
	ds_write_b128 v161, v[88:91] offset:8192
	s_waitcnt vmcnt(4)
	ds_write_b128 v161, v[92:95] offset:12288
	s_waitcnt vmcnt(3)
	ds_write_b128 v167, v[220:223] offset:16384
	s_waitcnt vmcnt(2)
	ds_write_b128 v167, v[224:227] offset:20480
	s_waitcnt vmcnt(1)
	ds_write_b128 v167, v[228:231] offset:24576
	s_waitcnt vmcnt(0)
	ds_write_b128 v167, v[232:235] offset:28672
	s_waitcnt lgkmcnt(0)
	s_barrier
	ds_read_b128 v[80:83], v170
	ds_read_b128 v[84:87], v170 offset:4096
	s_waitcnt lgkmcnt(1)
	v_mfma_f32_16x16x32_bf16 v[88:91], v[80:83], v[72:75], 0
	v_mfma_f32_16x16x32_bf16 v[92:95], v[80:83], v[76:79], 0
	s_waitcnt lgkmcnt(0)
	v_mfma_f32_16x16x32_bf16 v[100:103], v[84:87], v[72:75], 0
	v_mfma_f32_16x16x32_bf16 v[104:107], v[84:87], v[76:79], 0
	ds_read_b128 v[80:83], v170 offset:8192
	ds_read_b128 v[84:87], v170 offset:12288
	s_waitcnt lgkmcnt(1)
	v_mfma_f32_16x16x32_bf16 v[108:111], v[80:83], v[72:75], 0
	s_waitcnt lgkmcnt(0)
	v_mfma_f32_16x16x32_bf16 v[116:119], v[84:87], v[72:75], 0
	ds_read_b128 v[72:75], v171
	ds_read_b128 v[124:127], v171 offset:4096
	ds_read_b128 v[150:153], v171 offset:12288
	v_mfma_f32_16x16x32_bf16 v[112:115], v[80:83], v[76:79], 0
	s_waitcnt lgkmcnt(2)
	v_mfma_f32_16x16x32_bf16 v[80:83], v[72:75], v[68:71], v[88:91]
	s_nop 2
	ds_read_b128 v[88:91], v171 offset:8192
	v_mfma_f32_16x16x32_bf16 v[120:123], v[84:87], v[76:79], 0
	s_waitcnt lgkmcnt(2)
	v_mfma_f32_16x16x32_bf16 v[76:79], v[124:127], v[68:71], v[100:103]
	v_mfma_f32_16x16x32_bf16 v[84:87], v[72:75], v[64:67], v[92:95]
	s_nop 1
	v_add_f32_e32 v100, 0x41000000, v141
	v_max_f32_e32 v92, v81, v81
	v_max_f32_e32 v93, v80, v80
	s_waitcnt lgkmcnt(0)
	v_mfma_f32_16x16x32_bf16 v[72:75], v[88:91], v[68:71], v[108:111]
	v_max_f32_e32 v92, v93, v92
	v_max3_f32 v92, v92, v82, v83
	v_max3_f32 v92, v92, v76, v77
	v_mfma_f32_16x16x32_bf16 v[68:71], v[150:153], v[68:71], v[116:119]
	v_max3_f32 v92, v92, v78, v79
	s_nop 2
	v_max3_f32 v92, v92, v72, v73
	v_max3_f32 v92, v92, v74, v75
	v_mfma_f32_16x16x32_bf16 v[88:91], v[88:91], v[64:67], v[112:115]
	s_nop 0
	v_max3_f32 v92, v92, v68, v69
	v_max3_f32 v92, v92, v70, v71
	v_mul_f32_e32 v96, 0x3e38aa3b, v92
	ds_bpermute_b32 v98, v139, v96
	v_mfma_f32_16x16x32_bf16 v[92:95], v[124:127], v[64:67], v[104:107]
	s_waitcnt lgkmcnt(0)
	v_max_f32_e32 v98, v98, v98
	v_max_f32_e32 v96, v96, v98
	ds_bpermute_b32 v98, v135, v96
	v_mfma_f32_16x16x32_bf16 v[64:67], v[150:153], v[64:67], v[120:123]
	s_waitcnt lgkmcnt(0)
	v_max_f32_e32 v98, v98, v98
	v_max_f32_e32 v96, v96, v98
	v_cmp_gt_f32_e32 vcc, v96, v100
	s_nop 1
	v_cndmask_b32_e32 v100, v141, v96, vcc
	v_sub_f32_e32 v96, v141, v100
	v_exp_f32_e32 v96, v96
	s_nop 0
	v_cndmask_b32_e32 v96, 1.0, v96, vcc
	s_cbranch_vccz .LBB0_621
	v_pk_mul_f32 v[62:63], v[62:63], v[96:97] op_sel_hi:[1,0]
	v_pk_mul_f32 v[60:61], v[60:61], v[96:97] op_sel_hi:[1,0]
	v_pk_mul_f32 v[54:55], v[54:55], v[96:97] op_sel_hi:[1,0]
	v_pk_mul_f32 v[52:53], v[52:53], v[96:97] op_sel_hi:[1,0]
	v_pk_mul_f32 v[50:51], v[50:51], v[96:97] op_sel_hi:[1,0]
	v_pk_mul_f32 v[48:49], v[48:49], v[96:97] op_sel_hi:[1,0]
	v_pk_mul_f32 v[38:39], v[38:39], v[96:97] op_sel_hi:[1,0]
	v_pk_mul_f32 v[36:37], v[36:37], v[96:97] op_sel_hi:[1,0]
	v_pk_mul_f32 v[34:35], v[34:35], v[96:97] op_sel_hi:[1,0]
	v_pk_mul_f32 v[32:33], v[32:33], v[96:97] op_sel_hi:[1,0]
	v_pk_mul_f32 v[22:23], v[22:23], v[96:97] op_sel_hi:[1,0]
	v_pk_mul_f32 v[20:21], v[20:21], v[96:97] op_sel_hi:[1,0]
	v_pk_mul_f32 v[14:15], v[14:15], v[96:97] op_sel_hi:[1,0]
	v_pk_mul_f32 v[12:13], v[12:13], v[96:97] op_sel_hi:[1,0]
	v_pk_mul_f32 v[2:3], v[2:3], v[96:97] op_sel_hi:[1,0]
	v_pk_mul_f32 v[0:1], v[0:1], v[96:97] op_sel_hi:[1,0]

.LBB0_1985:
	s_add_u32 s12, s64, s26
	v_add_u32_e32 v146, s41, v157
	s_addc_u32 s26, s65, s27
	v_ashrrev_i32_e32 v147, 31, v146
	s_add_u32 s24, s12, s24
	v_lshlrev_b64 v[0:1], 11, v[146:147]
	s_addc_u32 s25, s26, s25
	v_lshl_add_u64 v[0:1], s[14:15], 0, v[0:1]
	s_lshl_b32 s12, s39, 8
	v_lshl_add_u64 v[0:1], v[0:1], 0, s[12:13]
	v_lshl_add_u64 v[0:1], v[0:1], 0, v[128:129]
	v_mov_b32_e32 v137, v129
	v_lshl_add_u64 v[0:1], v[0:1], 0, v[136:137]
	global_load_dwordx4 v[72:75], v[0:1], off
	global_load_dwordx4 v[68:71], v[0:1], off offset:64
	v_add_co_u32_e32 v0, vcc, s29, v0
	v_mov_b32_e32 v139, v129
	s_nop 0
	v_addc_co_u32_e32 v1, vcc, 0, v1, vcc
	global_load_dwordx4 v[76:79], v[0:1], off
	global_load_dwordx4 v[64:67], v[0:1], off offset:64
	v_lshl_add_u64 v[0:1], s[8:9], 0, v[138:139]
	v_mov_b32_e32 v141, v129
	v_lshl_add_u64 v[148:149], v[0:1], 0, v[140:141]
	v_add_co_u32_e32 v0, vcc, s30, v148
	global_load_dwordx4 v[80:83], v[148:149], off
	s_nop 0
	v_addc_co_u32_e32 v1, vcc, 0, v149, vcc
	v_add_co_u32_e32 v2, vcc, s31, v148
	global_load_dwordx4 v[88:91], v[0:1], off
	s_nop 0
	v_addc_co_u32_e32 v3, vcc, 0, v149, vcc
	global_load_dwordx4 v[84:87], v[0:1], off offset:-4096
	global_load_dwordx4 v[92:95], v[2:3], off
	v_mul_u32_u24_e32 v0, s40, v145
	v_lshlrev_b32_e32 v0, 1, v0
	v_mov_b32_e32 v1, v129
	v_lshl_add_u64 v[0:1], s[24:25], 0, v[0:1]
	v_mov_b32_e32 v143, v129
	v_cmp_lt_i32_e32 vcc, v168, v169
	v_lshl_add_u64 v[150:151], v[0:1], 0, v[142:143]
	s_lshl_b32 s8, s40, 8
	v_cndmask_b32_e32 v0, v155, v168, vcc
	v_cmp_lt_i32_e32 vcc, v170, v169
	v_lshlrev_b32_e32 v137, 2, v0
	v_mov_b32_e32 v8, v129
	v_cndmask_b32_e32 v0, v155, v170, vcc
	v_mov_b32_e32 v9, v129
	v_mov_b32_e32 v10, v129
	v_mov_b32_e32 v11, v129
	v_lshlrev_b32_e32 v133, 2, v0
	s_and_b32 s8, s8, 0x7c000
	v_mov_b64_e32 v[26:27], v[10:11]
	v_mov_b64_e32 v[30:31], v[10:11]
	v_mov_b64_e32 v[42:43], v[10:11]
	v_mov_b64_e32 v[46:47], v[10:11]
	v_mov_b64_e32 v[58:59], v[10:11]
	v_mov_b64_e32 v[0:1], v[8:9]
	v_mov_b64_e32 v[14:15], v[10:11]
	v_mov_b64_e32 v[22:23], v[10:11]
	v_mov_b64_e32 v[34:35], v[10:11]
	v_mov_b64_e32 v[38:39], v[10:11]
	v_mov_b64_e32 v[50:51], v[10:11]
	v_mov_b64_e32 v[54:55], v[10:11]
	v_mov_b64_e32 v[62:63], v[10:11]
	v_mov_b64_e32 v[18:19], v[10:11]
	v_mov_b64_e32 v[4:5], v[8:9]
	s_lshl_b32 s39, s39, 7
	s_lshl_b32 s12, s40, 6
	s_add_u32 s41, s8, 0xffffc000
	s_lshl_b32 s8, s40, 7
	s_mov_b32 s9, s13
	s_mul_i32 s24, s40, 0xc0
	s_mov_b32 s25, s13
	v_mov_b32_e32 v143, 0
	v_mov_b32_e32 v156, 0xf149f2ca
	s_mov_b64 s[26:27], 0
	v_mov_b64_e32 v[152:153], v[150:151]
	v_mov_b64_e32 v[24:25], v[8:9]
	v_mov_b64_e32 v[28:29], v[8:9]
	v_mov_b64_e32 v[40:41], v[8:9]
	v_mov_b64_e32 v[44:45], v[8:9]
	v_mov_b64_e32 v[56:57], v[8:9]
	v_mov_b64_e32 v[2:3], v[10:11]
	v_mov_b64_e32 v[12:13], v[8:9]
	v_mov_b64_e32 v[20:21], v[8:9]
	v_mov_b64_e32 v[32:33], v[8:9]
	v_mov_b64_e32 v[36:37], v[8:9]
	v_mov_b64_e32 v[48:49], v[8:9]
	v_mov_b64_e32 v[52:53], v[8:9]
	v_mov_b64_e32 v[60:61], v[8:9]
	v_mov_b32_e32 v139, 0xf149f2ca
	v_mov_b32_e32 v141, 0
	v_mov_b64_e32 v[16:17], v[8:9]
	v_mov_b64_e32 v[6:7], v[10:11]
	global_load_dwordx4 v[220:223], v[152:153], off
	v_lshl_add_u64 v[236:237], v[152:153], 0, s[12:13]
	global_load_dwordx4 v[224:227], v[236:237], off
	v_lshl_add_u64 v[236:237], v[152:153], 0, s[8:9]
	global_load_dwordx4 v[228:231], v[236:237], off
	v_lshl_add_u64 v[236:237], v[152:153], 0, s[24:25]
	global_load_dwordx4 v[232:235], v[236:237], off
.LBB0_1986:
	s_barrier
	s_waitcnt vmcnt(7)
	ds_write_b128 v159, v[80:83]
	s_waitcnt vmcnt(5)
	ds_write_b128 v159, v[84:87] offset:4096
	ds_write_b128 v159, v[88:91] offset:8192
	s_waitcnt vmcnt(4)
	ds_write_b128 v159, v[92:95] offset:12288
	s_waitcnt vmcnt(3)
	ds_write_b128 v160, v[220:223] offset:16384
	s_waitcnt vmcnt(2)
	ds_write_b128 v160, v[224:227] offset:20480
	s_waitcnt vmcnt(1)
	ds_write_b128 v160, v[228:231] offset:24576
	s_waitcnt vmcnt(0)
	ds_write_b128 v160, v[232:235] offset:28672
	s_waitcnt lgkmcnt(0)
	s_barrier
	ds_read_b128 v[80:83], v161
	ds_read_b128 v[84:87], v161 offset:4096
	s_waitcnt lgkmcnt(0)
	v_mfma_f32_16x16x32_bf16 v[92:95], v[84:87], v[72:75], 0
	v_mfma_f32_16x16x32_bf16 v[104:107], v[84:87], v[76:79], 0
	ds_read_b128 v[84:87], v161 offset:8192
	ds_read_b128 v[96:99], v161 offset:12288
	ds_read_b128 v[180:183], v166 offset:4096
	ds_read_b128 v[184:187], v166 offset:8192
	s_waitcnt lgkmcnt(3)
	v_mfma_f32_16x16x32_bf16 v[100:103], v[84:87], v[72:75], 0
	v_mfma_f32_16x16x32_bf16 v[120:123], v[84:87], v[76:79], 0
	ds_read_b128 v[84:87], v166
	v_mfma_f32_16x16x32_bf16 v[88:91], v[80:83], v[72:75], 0
	s_waitcnt lgkmcnt(3)
	v_mfma_f32_16x16x32_bf16 v[124:127], v[96:99], v[72:75], 0
	v_mfma_f32_16x16x32_bf16 v[176:179], v[96:99], v[76:79], 0
	v_lshl_add_u64 v[96:97], v[148:149], 0, s[26:27]
	v_mfma_f32_16x16x32_bf16 v[80:83], v[80:83], v[76:79], 0
	s_waitcnt lgkmcnt(0)
	v_mfma_f32_16x16x32_bf16 v[112:115], v[84:87], v[68:71], v[88:91]
	s_nop 2
	v_add_co_u32_e32 v88, vcc, s34, v96
	v_mfma_f32_16x16x32_bf16 v[116:119], v[84:87], v[64:67], v[80:83]
	s_nop 0
	v_addc_co_u32_e32 v89, vcc, 0, v97, vcc
	v_add_co_u32_e32 v96, vcc, s35, v96
	v_mfma_f32_16x16x32_bf16 v[108:111], v[180:183], v[68:71], v[92:95]
	s_nop 0
	v_addc_co_u32_e32 v97, vcc, 0, v97, vcc
	global_load_dwordx4 v[80:83], v[88:89], off offset:-4096
	global_load_dwordx4 v[84:87], v[88:89], off
	ds_read_b128 v[188:191], v166 offset:12288
	global_load_dwordx4 v[88:91], v[96:97], off offset:-4096
	global_load_dwordx4 v[92:95], v[96:97], off
	global_load_dwordx4 v[220:223], v[152:153], off offset:128
	v_lshl_add_u64 v[236:237], v[152:153], 0, s[12:13]
	global_load_dwordx4 v[224:227], v[236:237], off offset:128
	v_lshl_add_u64 v[236:237], v[152:153], 0, s[8:9]
	global_load_dwordx4 v[228:231], v[236:237], off offset:128
	v_lshl_add_u64 v[236:237], v[152:153], 0, s[24:25]
	global_load_dwordx4 v[232:235], v[236:237], off offset:128
	s_waitcnt lgkmcnt(0)
	v_mfma_f32_16x16x32_bf16 v[96:99], v[188:191], v[68:71], v[124:127]
	s_nop 2
	v_max_f32_e32 v124, v113, v113
	v_max_f32_e32 v125, v112, v112
	v_max_f32_e32 v124, v125, v124
	v_mfma_f32_16x16x32_bf16 v[100:103], v[184:187], v[68:71], v[100:103]
	v_max3_f32 v124, v124, v114, v115
	v_max3_f32 v124, v124, v108, v109
	v_max3_f32 v124, v124, v110, v111
	v_mfma_f32_16x16x32_bf16 v[120:123], v[184:187], v[64:67], v[120:123]
	s_nop 3
	v_max3_f32 v124, v124, v100, v101
	v_max3_f32 v124, v124, v102, v103
	v_max3_f32 v124, v124, v96, v97
	v_max3_f32 v124, v124, v98, v99
	v_mul_f32_e32 v154, 0x3e38aa3b, v124
	ds_bpermute_b32 v192, v137, v154
	v_mfma_f32_16x16x32_bf16 v[124:127], v[180:183], v[64:67], v[104:107]
	s_waitcnt lgkmcnt(0)
	s_nop 1
	v_max_f32_e32 v104, v192, v192
	v_max_f32_e32 v104, v154, v104
	ds_bpermute_b32 v105, v133, v104
	v_mov_b32_e32 v106, v139
	s_waitcnt lgkmcnt(0)
	v_max_f32_e32 v105, v105, v105
	v_max_f32_e32 v104, v104, v105
	v_add_f32_e32 v105, 0x41000000, v106
	v_cmp_gt_f32_e32 vcc, v104, v105
	s_nop 1
	v_cndmask_b32_e32 v139, v106, v104, vcc
	v_sub_f32_e32 v104, v106, v139
	v_exp_f32_e32 v154, v104
	v_mfma_f32_16x16x32_bf16 v[104:107], v[188:191], v[64:67], v[176:179]
	v_cndmask_b32_e32 v154, 1.0, v154, vcc
	s_cbranch_vccz .LBB0_1988
	v_pk_mul_f32 v[62:63], v[62:63], v[154:155] op_sel_hi:[1,0]
	v_pk_mul_f32 v[60:61], v[60:61], v[154:155] op_sel_hi:[1,0]
	v_pk_mul_f32 v[54:55], v[54:55], v[154:155] op_sel_hi:[1,0]
	v_pk_mul_f32 v[52:53], v[52:53], v[154:155] op_sel_hi:[1,0]
	v_pk_mul_f32 v[50:51], v[50:51], v[154:155] op_sel_hi:[1,0]
	v_pk_mul_f32 v[48:49], v[48:49], v[154:155] op_sel_hi:[1,0]
	v_pk_mul_f32 v[38:39], v[38:39], v[154:155] op_sel_hi:[1,0]
	v_pk_mul_f32 v[36:37], v[36:37], v[154:155] op_sel_hi:[1,0]
	v_pk_mul_f32 v[34:35], v[34:35], v[154:155] op_sel_hi:[1,0]
	v_pk_mul_f32 v[32:33], v[32:33], v[154:155] op_sel_hi:[1,0]
	v_pk_mul_f32 v[22:23], v[22:23], v[154:155] op_sel_hi:[1,0]
	v_pk_mul_f32 v[20:21], v[20:21], v[154:155] op_sel_hi:[1,0]
	v_pk_mul_f32 v[14:15], v[14:15], v[154:155] op_sel_hi:[1,0]
	v_pk_mul_f32 v[12:13], v[12:13], v[154:155] op_sel_hi:[1,0]
	v_pk_mul_f32 v[2:3], v[2:3], v[154:155] op_sel_hi:[1,0]
	v_pk_mul_f32 v[0:1], v[0:1], v[154:155] op_sel_hi:[1,0]

.LBB0_1992:
	s_and_b32 s8, s40, 0x7c0
	s_sub_i32 s8, s8, 64
	s_mov_b32 s9, s13
	v_lshl_add_u64 v[100:101], s[8:9], 1, v[150:151]
	v_lshl_add_u64 v[108:109], v[100:101], 0, s[12:13]
	s_barrier
	s_nop 0
	v_lshl_add_u64 v[108:109], v[108:109], 0, s[12:13]
	v_lshl_add_u64 v[112:113], v[108:109], 0, s[12:13]
	s_nop 0
	s_waitcnt vmcnt(7)
	ds_write_b128 v159, v[80:83]
	s_waitcnt vmcnt(6)
	ds_write_b128 v159, v[84:87] offset:4096
	s_waitcnt vmcnt(5)
	ds_write_b128 v159, v[88:91] offset:8192
	s_waitcnt vmcnt(4)
	ds_write_b128 v159, v[92:95] offset:12288
	s_waitcnt vmcnt(3)
	ds_write_b128 v160, v[220:223] offset:16384
	s_waitcnt vmcnt(2)
	ds_write_b128 v160, v[224:227] offset:20480
	s_waitcnt vmcnt(1)
	ds_write_b128 v160, v[228:231] offset:24576
	s_waitcnt vmcnt(0)
	ds_write_b128 v160, v[232:235] offset:28672
	s_waitcnt lgkmcnt(0)
	s_barrier
	ds_read_b128 v[80:83], v161
	ds_read_b128 v[84:87], v161 offset:4096
	s_waitcnt lgkmcnt(1)
	v_mfma_f32_16x16x32_bf16 v[88:91], v[80:83], v[72:75], 0
	v_mfma_f32_16x16x32_bf16 v[92:95], v[80:83], v[76:79], 0
	s_waitcnt lgkmcnt(0)
	v_mfma_f32_16x16x32_bf16 v[100:103], v[84:87], v[72:75], 0
	v_mfma_f32_16x16x32_bf16 v[104:107], v[84:87], v[76:79], 0
	ds_read_b128 v[80:83], v161 offset:8192
	ds_read_b128 v[84:87], v161 offset:12288
	s_waitcnt lgkmcnt(1)
	v_mfma_f32_16x16x32_bf16 v[108:111], v[80:83], v[72:75], 0
	s_waitcnt lgkmcnt(0)
	v_mfma_f32_16x16x32_bf16 v[116:119], v[84:87], v[72:75], 0
	ds_read_b128 v[72:75], v166
	ds_read_b128 v[124:127], v166 offset:4096
	ds_read_b128 v[148:151], v166 offset:12288
	v_mfma_f32_16x16x32_bf16 v[112:115], v[80:83], v[76:79], 0
	s_waitcnt lgkmcnt(2)
	v_mfma_f32_16x16x32_bf16 v[80:83], v[72:75], v[68:71], v[88:91]
	s_nop 2
	ds_read_b128 v[88:91], v166 offset:8192
	v_mfma_f32_16x16x32_bf16 v[120:123], v[84:87], v[76:79], 0
	s_waitcnt lgkmcnt(2)
	v_mfma_f32_16x16x32_bf16 v[76:79], v[124:127], v[68:71], v[100:103]
	v_mfma_f32_16x16x32_bf16 v[84:87], v[72:75], v[64:67], v[92:95]
	s_nop 1
	v_add_f32_e32 v100, 0x41000000, v139
	v_max_f32_e32 v92, v81, v81
	v_max_f32_e32 v93, v80, v80
	s_waitcnt lgkmcnt(0)
	v_mfma_f32_16x16x32_bf16 v[72:75], v[88:91], v[68:71], v[108:111]
	v_max_f32_e32 v92, v93, v92
	v_max3_f32 v92, v92, v82, v83
	v_max3_f32 v92, v92, v76, v77
	v_mfma_f32_16x16x32_bf16 v[68:71], v[148:151], v[68:71], v[116:119]
	v_max3_f32 v92, v92, v78, v79
	s_nop 2
	v_max3_f32 v92, v92, v72, v73
	v_max3_f32 v92, v92, v74, v75
	v_mfma_f32_16x16x32_bf16 v[88:91], v[88:91], v[64:67], v[112:115]
	s_nop 0
	v_max3_f32 v92, v92, v68, v69
	v_max3_f32 v92, v92, v70, v71
	v_mul_f32_e32 v96, 0x3e38aa3b, v92
	ds_bpermute_b32 v98, v137, v96
	v_mfma_f32_16x16x32_bf16 v[92:95], v[124:127], v[64:67], v[104:107]
	s_waitcnt lgkmcnt(0)
	v_max_f32_e32 v98, v98, v98
	v_max_f32_e32 v96, v96, v98
	ds_bpermute_b32 v98, v133, v96
	v_mfma_f32_16x16x32_bf16 v[64:67], v[148:151], v[64:67], v[120:123]
	s_waitcnt lgkmcnt(0)
	v_max_f32_e32 v98, v98, v98
	v_max_f32_e32 v96, v96, v98
	v_cmp_gt_f32_e32 vcc, v96, v100
	s_nop 1
	v_cndmask_b32_e32 v100, v139, v96, vcc
	v_sub_f32_e32 v96, v139, v100
	v_exp_f32_e32 v96, v96
	s_nop 0
	v_cndmask_b32_e32 v96, 1.0, v96, vcc
	s_cbranch_vccz .LBB0_1994
	v_pk_mul_f32 v[62:63], v[62:63], v[96:97] op_sel_hi:[1,0]
	v_pk_mul_f32 v[60:61], v[60:61], v[96:97] op_sel_hi:[1,0]
	v_pk_mul_f32 v[54:55], v[54:55], v[96:97] op_sel_hi:[1,0]
	v_pk_mul_f32 v[52:53], v[52:53], v[96:97] op_sel_hi:[1,0]
	v_pk_mul_f32 v[50:51], v[50:51], v[96:97] op_sel_hi:[1,0]
	v_pk_mul_f32 v[48:49], v[48:49], v[96:97] op_sel_hi:[1,0]
	v_pk_mul_f32 v[38:39], v[38:39], v[96:97] op_sel_hi:[1,0]
	v_pk_mul_f32 v[36:37], v[36:37], v[96:97] op_sel_hi:[1,0]
	v_pk_mul_f32 v[34:35], v[34:35], v[96:97] op_sel_hi:[1,0]
	v_pk_mul_f32 v[32:33], v[32:33], v[96:97] op_sel_hi:[1,0]
	v_pk_mul_f32 v[22:23], v[22:23], v[96:97] op_sel_hi:[1,0]
	v_pk_mul_f32 v[20:21], v[20:21], v[96:97] op_sel_hi:[1,0]
	v_pk_mul_f32 v[14:15], v[14:15], v[96:97] op_sel_hi:[1,0]
	v_pk_mul_f32 v[12:13], v[12:13], v[96:97] op_sel_hi:[1,0]
	v_pk_mul_f32 v[2:3], v[2:3], v[96:97] op_sel_hi:[1,0]
	v_pk_mul_f32 v[0:1], v[0:1], v[96:97] op_sel_hi:[1,0]
